# GU: next tile's first two k-steps of loads (A fragments + LDS-DMA B stages 0/1) issued before the LDS-free SwiGLU epilogue via scalar next-tile decode and pointer deltas; fast-path prologue only zeroe
# baseline (speedup 1.0000x reference)
.LBB0_1029:
	s_or_b64 exec, exec, s[0:1]
	v_readlane_b32 s0, v253, 0
	s_waitcnt lgkmcnt(0)
	s_barrier
	s_ashr_i32 s2, s0, 3
	s_mul_i32 s3, s25, 44
	s_cmp_ge_i32 s2, s3
	s_cbranch_scc1 .LBB0_1034
	v_readlane_b32 s4, v254, 41
	s_mul_i32 s1, s4, 0xb00000
	v_readlane_b32 s5, v254, 42
	s_add_u32 s4, s52, s1
	s_addc_u32 s5, s53, 0
	s_and_b32 s6, s0, 7
	s_mul_i32 s6, s6, s25
	s_mov_b32 s99, 0
.LBB0_1031:
	s_mul_hi_i32 s0, s2, 0x2e8ba2e9
	s_lshr_b32 s1, s0, 31
	s_ashr_i32 s0, s0, 6
	s_add_i32 s0, s0, s1
	s_lshl_b32 s1, s0, 3
	s_sub_i32 s7, s25, s1
	s_min_i32 s7, s7, 8
	s_abs_i32 s8, s7
	v_cvt_f32_u32_e32 v0, s8
	s_sub_i32 s11, 0, s8
	s_mulk_i32 s0, 0xfea0
	s_add_i32 s9, s0, s2
	v_rcp_iflag_f32_e32 v0, v0
	s_abs_i32 s0, s9
	s_xor_b32 s10, s9, s7
	s_ashr_i32 s10, s10, 31
	v_mul_f32_e32 v0, 0x4f7ffffe, v0
	v_cvt_u32_f32_e32 v0, v0
	v_mov_b32_e32 v237, v179
	v_readfirstlane_b32 s12, v0
	s_mul_i32 s11, s11, s12
	s_mul_hi_u32 s11, s12, s11
	s_add_i32 s12, s12, s11
	s_mul_hi_u32 s11, s0, s12
	s_mul_i32 s12, s11, s8
	s_sub_i32 s0, s0, s12
	s_add_i32 s13, s11, 1
	s_sub_i32 s12, s0, s8
	s_cmp_ge_u32 s0, s8
	s_cselect_b32 s11, s13, s11
	s_cselect_b32 s0, s12, s0
	s_add_i32 s12, s11, 1
	s_cmp_ge_u32 s0, s8
	s_cselect_b32 s0, s12, s11
	s_xor_b32 s0, s0, s10
	s_sub_i32 s0, s0, s10
	s_mul_i32 s7, s7, s0
	s_sub_i32 s7, s9, s7
	s_add_i32 s1, s1, s6
	v_ashrrev_i32_e32 v238, 6, v237
	s_add_i32 s7, s1, s7
	v_lshlrev_b32_e32 v0, 1, v238
	v_lshl_add_u32 v0, s7, 3, v0
	v_ashrrev_i32_e32 v1, 31, v0
	v_bfe_u32 v183, v237, 5, 1
	v_lshlrev_b64 v[0:1], 16, v[0:1]
	v_and_b32_e32 v239, 31, v237
	v_lshl_add_u64 v[0:1], s[64:65], 0, v[0:1]
	v_lshlrev_b32_e32 v176, 9, v183
	s_ashr_i32 s1, s0, 31
	v_lshl_add_u64 v[0:1], v[0:1], 0, v[176:177]
	v_lshlrev_b32_e32 v176, 4, v239
	v_ashrrev_i32_e32 v38, 2, v237
	s_lshl_b64 s[8:9], s[0:1], 18
	v_lshl_add_u64 v[184:185], v[0:1], 0, v[176:177]
	s_add_u32 s8, s4, s8
	v_lshlrev_b32_e32 v0, 5, v38
	v_lshlrev_b32_e32 v2, 3, v237
	s_addc_u32 s9, s5, s9
	v_ashrrev_i32_e32 v1, 31, v0
	v_and_b32_e32 v181, 24, v2
	v_lshl_add_u64 v[0:1], v[0:1], 1, s[8:9]
	v_lshlrev_b32_e32 v176, 1, v181
	v_lshl_add_u64 v[186:187], v[0:1], 0, v[176:177]
	s_movk_i32 s1, 0x2000
	v_add_co_u32_e32 v34, vcc, s1, v186
	v_mul_u32_u24_e32 v36, 40, v239
	s_nop 0
	v_addc_co_u32_e32 v35, vcc, 0, v187, vcc
	v_lshlrev_b32_e32 v37, 4, v183
	v_lshl_add_u32 v241, v36, 1, v37
	v_add_co_u32_e32 v36, vcc, s41, v184
	s_movk_i32 s8, 0x50
	s_nop 0
	v_addc_co_u32_e32 v37, vcc, 0, v185, vcc
	v_mad_u64_u32 v[188:189], s[8:9], v38, s8, v[176:177]
	v_and_b32_e32 v240, 63, v237
	v_lshrrev_b32_e32 v176, 6, v237
	v_lshlrev_b32_e32 v247, 11, v176
	s_nop 0
	v_readfirstlane_b32 vcc_lo, v247
	s_cmp_eq_u32 s99, 1
	s_cbranch_scc1 .Lg16_gu_fast
	v_bfe_u32 v247, v237, 4, 2
	v_lshlrev_b32_e32 v247, 1, v247
	v_mov_b32_e32 v176, 0x78
	v_lshrrev_b32_e32 v247, v247, v176
	v_and_b32_e32 v247, 3, v247
	v_and_b32_e32 v174, 3, v237
	v_xor_b32_e32 v247, v247, v174
	v_lshlrev_b32_e32 v247, 4, v247
	v_and_b32_e32 v172, 0xffffffcf, v186
	v_or_b32_e32 v172, v172, v247
	v_mov_b32_e32 v173, v187
	v_lshrrev_b32_e32 v176, 6, v237
	v_lshlrev_b32_e32 v247, 11, v176
	v_lshlrev_b32_e32 v176, 10, v176
	v_lshl_add_u64 v[172:173], v[172:173], 0, v[176:177]
	v_readfirstlane_b32 vcc_lo, v247
	v_bfe_u32 v247, v237, 4, 1
	v_lshlrev_b32_e32 v176, 9, v183
	v_lshl_add_u32 v176, v247, 8, v176
	v_lshl_add_u64 v[168:169], v[184:185], 0, v[176:177]
	v_mov_b32_e32 v176, s41
	v_lshl_add_u64 v[170:171], v[168:169], 0, v[176:177]
	v_mov_b32_e32 v176, 0x78
	v_bfe_u32 v247, v237, 2, 1
	v_lshlrev_b32_e32 v247, 2, v247
	v_lshrrev_b32_e32 v247, v247, v176
	v_and_b32_e32 v247, 3, v247
	v_bfe_u32 v174, v237, 4, 2
	v_xor_b32_e32 v247, v247, v174
	v_lshlrev_b32_e32 v247, 4, v247
	v_bfe_u32 v174, v237, 2, 2
	v_lshlrev_b32_e32 v174, 3, v174
	v_and_b32_e32 v175, 3, v237
	v_add_u32_e32 v174, v174, v175
	v_lshl_add_u32 v174, v174, 6, v247
	v_bfe_u32 v247, v237, 2, 1
	v_lshlrev_b32_e32 v247, 2, v247
	v_add_u32_e32 v247, 2, v247
	v_lshrrev_b32_e32 v247, v247, v176
	v_and_b32_e32 v247, 3, v247
	v_bfe_u32 v175, v237, 4, 2
	v_xor_b32_e32 v247, v247, v175
	v_lshlrev_b32_e32 v247, 4, v247
	v_and_b32_e32 v175, 0xffffffcf, v174
	v_add_u32_e32 v175, 0x100, v175
	v_or_b32_e32 v175, v175, v247
	s_mov_b32 s96, 0
	s_mov_b32 m0, vcc_lo
	v_lshl_add_u64 v[160:161], v[172:173], 0, s[96:97]
	global_load_lds_dwordx4 v[160:161], off
	global_load_lds_dwordx4 v[160:161], off offset:1024
	s_mov_b32 s96, 0
	v_lshl_add_u64 v[248:249], v[168:169], 0, s[96:97]
	v_lshl_add_u64 v[250:251], v[170:171], 0, s[96:97]
	global_load_dwordx4 v[128:131], v[248:249], off
	global_load_dwordx4 v[132:135], v[248:249], off offset:256
	global_load_dwordx4 v[136:139], v[250:251], off
	global_load_dwordx4 v[140:143], v[250:251], off offset:256
	s_movk_i32 s96, 0x2000
	s_add_i32 m0, vcc_lo, 8192
	v_lshl_add_u64 v[160:161], v[172:173], 0, s[96:97]
	global_load_lds_dwordx4 v[160:161], off
	global_load_lds_dwordx4 v[160:161], off offset:1024
	s_movk_i32 s96, 0x800
	v_lshl_add_u64 v[248:249], v[168:169], 0, s[96:97]
	v_lshl_add_u64 v[250:251], v[170:171], 0, s[96:97]
	global_load_dwordx4 v[144:147], v[248:249], off
	global_load_dwordx4 v[148:151], v[248:249], off offset:256
	global_load_dwordx4 v[152:155], v[250:251], off
	global_load_dwordx4 v[156:159], v[250:251], off offset:256
	v_mov_b32_e32 v0, 0
	v_mov_b32_e32 v1, 0
	v_mov_b32_e32 v2, 0
	v_mov_b32_e32 v3, 0
	v_mov_b32_e32 v4, 0
	v_mov_b32_e32 v5, 0
	v_mov_b32_e32 v6, 0
	v_mov_b32_e32 v7, 0
	v_mov_b32_e32 v8, 0
	v_mov_b32_e32 v9, 0
	v_mov_b32_e32 v10, 0
	v_mov_b32_e32 v11, 0
	v_mov_b32_e32 v12, 0
	v_mov_b32_e32 v13, 0
	v_mov_b32_e32 v14, 0
	v_mov_b32_e32 v15, 0
	v_mov_b32_e32 v16, 0
	v_mov_b32_e32 v17, 0
	v_mov_b32_e32 v18, 0
	v_mov_b32_e32 v19, 0
	v_mov_b32_e32 v20, 0
	v_mov_b32_e32 v21, 0
	v_mov_b32_e32 v22, 0
	v_mov_b32_e32 v23, 0
	v_mov_b32_e32 v24, 0
	v_mov_b32_e32 v25, 0
	v_mov_b32_e32 v26, 0
	v_mov_b32_e32 v27, 0
	v_mov_b32_e32 v28, 0
	v_mov_b32_e32 v29, 0
	v_mov_b32_e32 v30, 0
	v_mov_b32_e32 v31, 0
	v_mov_b32_e32 v32, 0
	v_mov_b32_e32 v33, 0
	v_mov_b32_e32 v34, 0
	v_mov_b32_e32 v35, 0
	v_mov_b32_e32 v36, 0
	v_mov_b32_e32 v37, 0
	v_mov_b32_e32 v38, 0
	v_mov_b32_e32 v39, 0
	v_mov_b32_e32 v40, 0
	v_mov_b32_e32 v41, 0
	v_mov_b32_e32 v42, 0
	v_mov_b32_e32 v43, 0
	v_mov_b32_e32 v44, 0
	v_mov_b32_e32 v45, 0
	v_mov_b32_e32 v46, 0
	v_mov_b32_e32 v47, 0
	v_mov_b32_e32 v48, 0
	v_mov_b32_e32 v49, 0
	v_mov_b32_e32 v50, 0
	v_mov_b32_e32 v51, 0
	v_mov_b32_e32 v52, 0
	v_mov_b32_e32 v53, 0
	v_mov_b32_e32 v54, 0
	v_mov_b32_e32 v55, 0
	v_mov_b32_e32 v56, 0
	v_mov_b32_e32 v57, 0
	v_mov_b32_e32 v58, 0
	v_mov_b32_e32 v59, 0
	v_mov_b32_e32 v60, 0
	v_mov_b32_e32 v61, 0
	v_mov_b32_e32 v62, 0
	v_mov_b32_e32 v63, 0
	v_mov_b32_e32 v64, 0
	v_mov_b32_e32 v65, 0
	v_mov_b32_e32 v66, 0
	v_mov_b32_e32 v67, 0
	v_mov_b32_e32 v68, 0
	v_mov_b32_e32 v69, 0
	v_mov_b32_e32 v70, 0
	v_mov_b32_e32 v71, 0
	v_mov_b32_e32 v72, 0
	v_mov_b32_e32 v73, 0
	v_mov_b32_e32 v74, 0
	v_mov_b32_e32 v75, 0
	v_mov_b32_e32 v76, 0
	v_mov_b32_e32 v77, 0
	v_mov_b32_e32 v78, 0
	v_mov_b32_e32 v79, 0
	v_mov_b32_e32 v80, 0
	v_mov_b32_e32 v81, 0
	v_mov_b32_e32 v82, 0
	v_mov_b32_e32 v83, 0
	v_mov_b32_e32 v84, 0
	v_mov_b32_e32 v85, 0
	v_mov_b32_e32 v86, 0
	v_mov_b32_e32 v87, 0
	v_mov_b32_e32 v88, 0
	v_mov_b32_e32 v89, 0
	v_mov_b32_e32 v90, 0
	v_mov_b32_e32 v91, 0
	v_mov_b32_e32 v92, 0
	v_mov_b32_e32 v93, 0
	v_mov_b32_e32 v94, 0
	v_mov_b32_e32 v95, 0
	v_mov_b32_e32 v96, 0
	v_mov_b32_e32 v97, 0
	v_mov_b32_e32 v98, 0
	v_mov_b32_e32 v99, 0
	v_mov_b32_e32 v100, 0
	v_mov_b32_e32 v101, 0
	v_mov_b32_e32 v102, 0
	v_mov_b32_e32 v103, 0
	v_mov_b32_e32 v104, 0
	v_mov_b32_e32 v105, 0
	v_mov_b32_e32 v106, 0
	v_mov_b32_e32 v107, 0
	v_mov_b32_e32 v108, 0
	v_mov_b32_e32 v109, 0
	v_mov_b32_e32 v110, 0
	v_mov_b32_e32 v111, 0
	v_mov_b32_e32 v112, 0
	v_mov_b32_e32 v113, 0
	v_mov_b32_e32 v114, 0
	v_mov_b32_e32 v115, 0
	v_mov_b32_e32 v116, 0
	v_mov_b32_e32 v117, 0
	v_mov_b32_e32 v118, 0
	v_mov_b32_e32 v119, 0
	v_mov_b32_e32 v120, 0
	v_mov_b32_e32 v121, 0
	v_mov_b32_e32 v122, 0
	v_mov_b32_e32 v123, 0
	v_mov_b32_e32 v124, 0
	v_mov_b32_e32 v125, 0
	v_mov_b32_e32 v126, 0
	v_mov_b32_e32 v127, 0
	s_mov_b32 s1, 0
	s_waitcnt vmcnt(4)
	s_barrier
	s_branch .Lg16_gu_go

.Lg16_gu_go:
.Lg16_gu_k:
	s_add_i32 s8, s1, 2
	s_lshl_b32 s96, s8, 13
	s_add_i32 m0, vcc_lo, 16384
	v_lshl_add_u64 v[160:161], v[172:173], 0, s[96:97]
	global_load_lds_dwordx4 v[160:161], off
	global_load_lds_dwordx4 v[160:161], off offset:1024
	ds_read_b128 v[196:199], v174 offset:0
	ds_read_b128 v[200:203], v175 offset:0
	ds_read_b128 v[204:207], v174 offset:2048
	ds_read_b128 v[242:245], v175 offset:2048
	s_add_i32 s8, s1, 2
	s_lshl_b32 s96, s8, 11
	v_lshl_add_u64 v[248:249], v[168:169], 0, s[96:97]
	v_lshl_add_u64 v[250:251], v[170:171], 0, s[96:97]
	s_waitcnt vmcnt(8) lgkmcnt(3)
	v_mfma_f32_16x16x32_bf16 v[112:115], v[196:199], v[128:131], v[112:115]
	v_mfma_f32_16x16x32_bf16 v[120:123], v[196:199], v[132:135], v[120:123]
	v_mfma_f32_16x16x32_bf16 v[80:83], v[196:199], v[136:139], v[80:83]
	v_mfma_f32_16x16x32_bf16 v[88:91], v[196:199], v[140:143], v[88:91]
	ds_read_b128 v[196:199], v174 offset:4096
	s_waitcnt lgkmcnt(3)
	v_mfma_f32_16x16x32_bf16 v[116:119], v[200:203], v[128:131], v[116:119]
	v_mfma_f32_16x16x32_bf16 v[124:127], v[200:203], v[132:135], v[124:127]
	v_mfma_f32_16x16x32_bf16 v[84:87], v[200:203], v[136:139], v[84:87]
	v_mfma_f32_16x16x32_bf16 v[92:95], v[200:203], v[140:143], v[92:95]
	ds_read_b128 v[200:203], v175 offset:4096
	s_waitcnt lgkmcnt(3)
	v_mfma_f32_16x16x32_bf16 v[96:99], v[204:207], v[128:131], v[96:99]
	v_mfma_f32_16x16x32_bf16 v[104:107], v[204:207], v[132:135], v[104:107]
	v_mfma_f32_16x16x32_bf16 v[64:67], v[204:207], v[136:139], v[64:67]
	v_mfma_f32_16x16x32_bf16 v[72:75], v[204:207], v[140:143], v[72:75]
	ds_read_b128 v[204:207], v174 offset:6144
	s_waitcnt lgkmcnt(3)
	v_mfma_f32_16x16x32_bf16 v[100:103], v[242:245], v[128:131], v[100:103]
	v_mfma_f32_16x16x32_bf16 v[108:111], v[242:245], v[132:135], v[108:111]
	v_mfma_f32_16x16x32_bf16 v[68:71], v[242:245], v[136:139], v[68:71]
	v_mfma_f32_16x16x32_bf16 v[76:79], v[242:245], v[140:143], v[76:79]
	ds_read_b128 v[242:245], v175 offset:6144
	s_waitcnt lgkmcnt(3)
	v_mfma_f32_16x16x32_bf16 v[48:51], v[196:199], v[128:131], v[48:51]
	v_mfma_f32_16x16x32_bf16 v[56:59], v[196:199], v[132:135], v[56:59]
	v_mfma_f32_16x16x32_bf16 v[16:19], v[196:199], v[136:139], v[16:19]
	v_mfma_f32_16x16x32_bf16 v[24:27], v[196:199], v[140:143], v[24:27]
	s_waitcnt lgkmcnt(2)
	v_mfma_f32_16x16x32_bf16 v[52:55], v[200:203], v[128:131], v[52:55]
	v_mfma_f32_16x16x32_bf16 v[60:63], v[200:203], v[132:135], v[60:63]
	v_mfma_f32_16x16x32_bf16 v[20:23], v[200:203], v[136:139], v[20:23]
	v_mfma_f32_16x16x32_bf16 v[28:31], v[200:203], v[140:143], v[28:31]
	s_waitcnt lgkmcnt(1)
	v_mfma_f32_16x16x32_bf16 v[32:35], v[204:207], v[128:131], v[32:35]
	v_mfma_f32_16x16x32_bf16 v[40:43], v[204:207], v[132:135], v[40:43]
	v_mfma_f32_16x16x32_bf16 v[0:3], v[204:207], v[136:139], v[0:3]
	v_mfma_f32_16x16x32_bf16 v[8:11], v[204:207], v[140:143], v[8:11]
	s_waitcnt lgkmcnt(0)
	v_mfma_f32_16x16x32_bf16 v[36:39], v[242:245], v[128:131], v[36:39]
	v_mfma_f32_16x16x32_bf16 v[44:47], v[242:245], v[132:135], v[44:47]
	v_mfma_f32_16x16x32_bf16 v[4:7], v[242:245], v[136:139], v[4:7]
	v_mfma_f32_16x16x32_bf16 v[12:15], v[242:245], v[140:143], v[12:15]
	global_load_dwordx4 v[128:131], v[248:249], off
	global_load_dwordx4 v[132:135], v[248:249], off offset:256
	global_load_dwordx4 v[136:139], v[250:251], off
	global_load_dwordx4 v[140:143], v[250:251], off offset:256
	s_waitcnt vmcnt(10)
	s_barrier
	s_add_i32 s8, s1, 3
	s_lshl_b32 s96, s8, 13
	s_mov_b32 m0, vcc_lo
	v_lshl_add_u64 v[160:161], v[172:173], 0, s[96:97]
	global_load_lds_dwordx4 v[160:161], off
	global_load_lds_dwordx4 v[160:161], off offset:1024
	ds_read_b128 v[196:199], v174 offset:8192
	ds_read_b128 v[200:203], v175 offset:8192
	ds_read_b128 v[204:207], v174 offset:10240
	ds_read_b128 v[242:245], v175 offset:10240
	s_add_i32 s8, s1, 3
	s_lshl_b32 s96, s8, 11
	v_lshl_add_u64 v[248:249], v[168:169], 0, s[96:97]
	v_lshl_add_u64 v[250:251], v[170:171], 0, s[96:97]
	s_waitcnt vmcnt(8) lgkmcnt(3)
	v_mfma_f32_16x16x32_bf16 v[112:115], v[196:199], v[144:147], v[112:115]
	v_mfma_f32_16x16x32_bf16 v[120:123], v[196:199], v[148:151], v[120:123]
	v_mfma_f32_16x16x32_bf16 v[80:83], v[196:199], v[152:155], v[80:83]
	v_mfma_f32_16x16x32_bf16 v[88:91], v[196:199], v[156:159], v[88:91]
	ds_read_b128 v[196:199], v174 offset:12288
	s_waitcnt lgkmcnt(3)
	v_mfma_f32_16x16x32_bf16 v[116:119], v[200:203], v[144:147], v[116:119]
	v_mfma_f32_16x16x32_bf16 v[124:127], v[200:203], v[148:151], v[124:127]
	v_mfma_f32_16x16x32_bf16 v[84:87], v[200:203], v[152:155], v[84:87]
	v_mfma_f32_16x16x32_bf16 v[92:95], v[200:203], v[156:159], v[92:95]
	ds_read_b128 v[200:203], v175 offset:12288
	s_waitcnt lgkmcnt(3)
	v_mfma_f32_16x16x32_bf16 v[96:99], v[204:207], v[144:147], v[96:99]
	v_mfma_f32_16x16x32_bf16 v[104:107], v[204:207], v[148:151], v[104:107]
	v_mfma_f32_16x16x32_bf16 v[64:67], v[204:207], v[152:155], v[64:67]
	v_mfma_f32_16x16x32_bf16 v[72:75], v[204:207], v[156:159], v[72:75]
	ds_read_b128 v[204:207], v174 offset:14336
	s_waitcnt lgkmcnt(3)
	v_mfma_f32_16x16x32_bf16 v[100:103], v[242:245], v[144:147], v[100:103]
	v_mfma_f32_16x16x32_bf16 v[108:111], v[242:245], v[148:151], v[108:111]
	v_mfma_f32_16x16x32_bf16 v[68:71], v[242:245], v[152:155], v[68:71]
	v_mfma_f32_16x16x32_bf16 v[76:79], v[242:245], v[156:159], v[76:79]
	ds_read_b128 v[242:245], v175 offset:14336
	s_waitcnt lgkmcnt(3)
	v_mfma_f32_16x16x32_bf16 v[48:51], v[196:199], v[144:147], v[48:51]
	v_mfma_f32_16x16x32_bf16 v[56:59], v[196:199], v[148:151], v[56:59]
	v_mfma_f32_16x16x32_bf16 v[16:19], v[196:199], v[152:155], v[16:19]
	v_mfma_f32_16x16x32_bf16 v[24:27], v[196:199], v[156:159], v[24:27]
	s_waitcnt lgkmcnt(2)
	v_mfma_f32_16x16x32_bf16 v[52:55], v[200:203], v[144:147], v[52:55]
	v_mfma_f32_16x16x32_bf16 v[60:63], v[200:203], v[148:151], v[60:63]
	v_mfma_f32_16x16x32_bf16 v[20:23], v[200:203], v[152:155], v[20:23]
	v_mfma_f32_16x16x32_bf16 v[28:31], v[200:203], v[156:159], v[28:31]
	s_waitcnt lgkmcnt(1)
	v_mfma_f32_16x16x32_bf16 v[32:35], v[204:207], v[144:147], v[32:35]
	v_mfma_f32_16x16x32_bf16 v[40:43], v[204:207], v[148:151], v[40:43]
	v_mfma_f32_16x16x32_bf16 v[0:3], v[204:207], v[152:155], v[0:3]
	v_mfma_f32_16x16x32_bf16 v[8:11], v[204:207], v[156:159], v[8:11]
	s_waitcnt lgkmcnt(0)
	v_mfma_f32_16x16x32_bf16 v[36:39], v[242:245], v[144:147], v[36:39]
	v_mfma_f32_16x16x32_bf16 v[44:47], v[242:245], v[148:151], v[44:47]
	v_mfma_f32_16x16x32_bf16 v[4:7], v[242:245], v[152:155], v[4:7]
	v_mfma_f32_16x16x32_bf16 v[12:15], v[242:245], v[156:159], v[12:15]
	global_load_dwordx4 v[144:147], v[248:249], off
	global_load_dwordx4 v[148:151], v[248:249], off offset:256
	global_load_dwordx4 v[152:155], v[250:251], off
	global_load_dwordx4 v[156:159], v[250:251], off offset:256
	s_waitcnt vmcnt(10)
	s_barrier
	s_add_i32 s8, s1, 4
	s_lshl_b32 s96, s8, 13
	s_add_i32 m0, vcc_lo, 8192
	v_lshl_add_u64 v[160:161], v[172:173], 0, s[96:97]
	global_load_lds_dwordx4 v[160:161], off
	global_load_lds_dwordx4 v[160:161], off offset:1024
	ds_read_b128 v[196:199], v174 offset:16384
	ds_read_b128 v[200:203], v175 offset:16384
	ds_read_b128 v[204:207], v174 offset:18432
	ds_read_b128 v[242:245], v175 offset:18432
	s_add_i32 s8, s1, 4
	s_lshl_b32 s96, s8, 11
	v_lshl_add_u64 v[248:249], v[168:169], 0, s[96:97]
	v_lshl_add_u64 v[250:251], v[170:171], 0, s[96:97]
	s_waitcnt vmcnt(8) lgkmcnt(3)
	v_mfma_f32_16x16x32_bf16 v[112:115], v[196:199], v[128:131], v[112:115]
	v_mfma_f32_16x16x32_bf16 v[120:123], v[196:199], v[132:135], v[120:123]
	v_mfma_f32_16x16x32_bf16 v[80:83], v[196:199], v[136:139], v[80:83]
	v_mfma_f32_16x16x32_bf16 v[88:91], v[196:199], v[140:143], v[88:91]
	ds_read_b128 v[196:199], v174 offset:20480
	s_waitcnt lgkmcnt(3)
	v_mfma_f32_16x16x32_bf16 v[116:119], v[200:203], v[128:131], v[116:119]
	v_mfma_f32_16x16x32_bf16 v[124:127], v[200:203], v[132:135], v[124:127]
	v_mfma_f32_16x16x32_bf16 v[84:87], v[200:203], v[136:139], v[84:87]
	v_mfma_f32_16x16x32_bf16 v[92:95], v[200:203], v[140:143], v[92:95]
	ds_read_b128 v[200:203], v175 offset:20480
	s_waitcnt lgkmcnt(3)
	v_mfma_f32_16x16x32_bf16 v[96:99], v[204:207], v[128:131], v[96:99]
	v_mfma_f32_16x16x32_bf16 v[104:107], v[204:207], v[132:135], v[104:107]
	v_mfma_f32_16x16x32_bf16 v[64:67], v[204:207], v[136:139], v[64:67]
	v_mfma_f32_16x16x32_bf16 v[72:75], v[204:207], v[140:143], v[72:75]
	ds_read_b128 v[204:207], v174 offset:22528
	s_waitcnt lgkmcnt(3)
	v_mfma_f32_16x16x32_bf16 v[100:103], v[242:245], v[128:131], v[100:103]
	v_mfma_f32_16x16x32_bf16 v[108:111], v[242:245], v[132:135], v[108:111]
	v_mfma_f32_16x16x32_bf16 v[68:71], v[242:245], v[136:139], v[68:71]
	v_mfma_f32_16x16x32_bf16 v[76:79], v[242:245], v[140:143], v[76:79]
	ds_read_b128 v[242:245], v175 offset:22528
	s_waitcnt lgkmcnt(3)
	v_mfma_f32_16x16x32_bf16 v[48:51], v[196:199], v[128:131], v[48:51]
	v_mfma_f32_16x16x32_bf16 v[56:59], v[196:199], v[132:135], v[56:59]
	v_mfma_f32_16x16x32_bf16 v[16:19], v[196:199], v[136:139], v[16:19]
	v_mfma_f32_16x16x32_bf16 v[24:27], v[196:199], v[140:143], v[24:27]
	s_waitcnt lgkmcnt(2)
	v_mfma_f32_16x16x32_bf16 v[52:55], v[200:203], v[128:131], v[52:55]
	v_mfma_f32_16x16x32_bf16 v[60:63], v[200:203], v[132:135], v[60:63]
	v_mfma_f32_16x16x32_bf16 v[20:23], v[200:203], v[136:139], v[20:23]
	v_mfma_f32_16x16x32_bf16 v[28:31], v[200:203], v[140:143], v[28:31]
	s_waitcnt lgkmcnt(1)
	v_mfma_f32_16x16x32_bf16 v[32:35], v[204:207], v[128:131], v[32:35]
	v_mfma_f32_16x16x32_bf16 v[40:43], v[204:207], v[132:135], v[40:43]
	v_mfma_f32_16x16x32_bf16 v[0:3], v[204:207], v[136:139], v[0:3]
	v_mfma_f32_16x16x32_bf16 v[8:11], v[204:207], v[140:143], v[8:11]
	s_waitcnt lgkmcnt(0)
	v_mfma_f32_16x16x32_bf16 v[36:39], v[242:245], v[128:131], v[36:39]
	v_mfma_f32_16x16x32_bf16 v[44:47], v[242:245], v[132:135], v[44:47]
	v_mfma_f32_16x16x32_bf16 v[4:7], v[242:245], v[136:139], v[4:7]
	v_mfma_f32_16x16x32_bf16 v[12:15], v[242:245], v[140:143], v[12:15]
	global_load_dwordx4 v[128:131], v[248:249], off
	global_load_dwordx4 v[132:135], v[248:249], off offset:256
	global_load_dwordx4 v[136:139], v[250:251], off
	global_load_dwordx4 v[140:143], v[250:251], off offset:256
	s_waitcnt vmcnt(10)
	s_barrier
	s_add_i32 s8, s1, 5
	s_lshl_b32 s96, s8, 13
	s_add_i32 m0, vcc_lo, 16384
	v_lshl_add_u64 v[160:161], v[172:173], 0, s[96:97]
	global_load_lds_dwordx4 v[160:161], off
	global_load_lds_dwordx4 v[160:161], off offset:1024
	ds_read_b128 v[196:199], v174 offset:0
	ds_read_b128 v[200:203], v175 offset:0
	ds_read_b128 v[204:207], v174 offset:2048
	ds_read_b128 v[242:245], v175 offset:2048
	s_add_i32 s8, s1, 5
	s_lshl_b32 s96, s8, 11
	v_lshl_add_u64 v[248:249], v[168:169], 0, s[96:97]
	v_lshl_add_u64 v[250:251], v[170:171], 0, s[96:97]
	s_waitcnt vmcnt(8) lgkmcnt(3)
	v_mfma_f32_16x16x32_bf16 v[112:115], v[196:199], v[144:147], v[112:115]
	v_mfma_f32_16x16x32_bf16 v[120:123], v[196:199], v[148:151], v[120:123]
	v_mfma_f32_16x16x32_bf16 v[80:83], v[196:199], v[152:155], v[80:83]
	v_mfma_f32_16x16x32_bf16 v[88:91], v[196:199], v[156:159], v[88:91]
	ds_read_b128 v[196:199], v174 offset:4096
	s_waitcnt lgkmcnt(3)
	v_mfma_f32_16x16x32_bf16 v[116:119], v[200:203], v[144:147], v[116:119]
	v_mfma_f32_16x16x32_bf16 v[124:127], v[200:203], v[148:151], v[124:127]
	v_mfma_f32_16x16x32_bf16 v[84:87], v[200:203], v[152:155], v[84:87]
	v_mfma_f32_16x16x32_bf16 v[92:95], v[200:203], v[156:159], v[92:95]
	ds_read_b128 v[200:203], v175 offset:4096
	s_waitcnt lgkmcnt(3)
	v_mfma_f32_16x16x32_bf16 v[96:99], v[204:207], v[144:147], v[96:99]
	v_mfma_f32_16x16x32_bf16 v[104:107], v[204:207], v[148:151], v[104:107]
	v_mfma_f32_16x16x32_bf16 v[64:67], v[204:207], v[152:155], v[64:67]
	v_mfma_f32_16x16x32_bf16 v[72:75], v[204:207], v[156:159], v[72:75]
	ds_read_b128 v[204:207], v174 offset:6144
	s_waitcnt lgkmcnt(3)
	v_mfma_f32_16x16x32_bf16 v[100:103], v[242:245], v[144:147], v[100:103]
	v_mfma_f32_16x16x32_bf16 v[108:111], v[242:245], v[148:151], v[108:111]
	v_mfma_f32_16x16x32_bf16 v[68:71], v[242:245], v[152:155], v[68:71]
	v_mfma_f32_16x16x32_bf16 v[76:79], v[242:245], v[156:159], v[76:79]
	ds_read_b128 v[242:245], v175 offset:6144
	s_waitcnt lgkmcnt(3)
	v_mfma_f32_16x16x32_bf16 v[48:51], v[196:199], v[144:147], v[48:51]
	v_mfma_f32_16x16x32_bf16 v[56:59], v[196:199], v[148:151], v[56:59]
	v_mfma_f32_16x16x32_bf16 v[16:19], v[196:199], v[152:155], v[16:19]
	v_mfma_f32_16x16x32_bf16 v[24:27], v[196:199], v[156:159], v[24:27]
	s_waitcnt lgkmcnt(2)
	v_mfma_f32_16x16x32_bf16 v[52:55], v[200:203], v[144:147], v[52:55]
	v_mfma_f32_16x16x32_bf16 v[60:63], v[200:203], v[148:151], v[60:63]
	v_mfma_f32_16x16x32_bf16 v[20:23], v[200:203], v[152:155], v[20:23]
	v_mfma_f32_16x16x32_bf16 v[28:31], v[200:203], v[156:159], v[28:31]
	s_waitcnt lgkmcnt(1)
	v_mfma_f32_16x16x32_bf16 v[32:35], v[204:207], v[144:147], v[32:35]
	v_mfma_f32_16x16x32_bf16 v[40:43], v[204:207], v[148:151], v[40:43]
	v_mfma_f32_16x16x32_bf16 v[0:3], v[204:207], v[152:155], v[0:3]
	v_mfma_f32_16x16x32_bf16 v[8:11], v[204:207], v[156:159], v[8:11]
	s_waitcnt lgkmcnt(0)
	v_mfma_f32_16x16x32_bf16 v[36:39], v[242:245], v[144:147], v[36:39]
	v_mfma_f32_16x16x32_bf16 v[44:47], v[242:245], v[148:151], v[44:47]
	v_mfma_f32_16x16x32_bf16 v[4:7], v[242:245], v[152:155], v[4:7]
	v_mfma_f32_16x16x32_bf16 v[12:15], v[242:245], v[156:159], v[12:15]
	global_load_dwordx4 v[144:147], v[248:249], off
	global_load_dwordx4 v[148:151], v[248:249], off offset:256
	global_load_dwordx4 v[152:155], v[250:251], off
	global_load_dwordx4 v[156:159], v[250:251], off offset:256
	s_waitcnt vmcnt(10)
	s_barrier
	s_add_i32 s8, s1, 6
	s_lshl_b32 s96, s8, 13
	s_mov_b32 m0, vcc_lo
	v_lshl_add_u64 v[160:161], v[172:173], 0, s[96:97]
	global_load_lds_dwordx4 v[160:161], off
	global_load_lds_dwordx4 v[160:161], off offset:1024
	ds_read_b128 v[196:199], v174 offset:8192
	ds_read_b128 v[200:203], v175 offset:8192
	ds_read_b128 v[204:207], v174 offset:10240
	ds_read_b128 v[242:245], v175 offset:10240
	s_add_i32 s8, s1, 6
	s_lshl_b32 s96, s8, 11
	v_lshl_add_u64 v[248:249], v[168:169], 0, s[96:97]
	v_lshl_add_u64 v[250:251], v[170:171], 0, s[96:97]
	s_waitcnt vmcnt(8) lgkmcnt(3)
	v_mfma_f32_16x16x32_bf16 v[112:115], v[196:199], v[128:131], v[112:115]
	v_mfma_f32_16x16x32_bf16 v[120:123], v[196:199], v[132:135], v[120:123]
	v_mfma_f32_16x16x32_bf16 v[80:83], v[196:199], v[136:139], v[80:83]
	v_mfma_f32_16x16x32_bf16 v[88:91], v[196:199], v[140:143], v[88:91]
	ds_read_b128 v[196:199], v174 offset:12288
	s_waitcnt lgkmcnt(3)
	v_mfma_f32_16x16x32_bf16 v[116:119], v[200:203], v[128:131], v[116:119]
	v_mfma_f32_16x16x32_bf16 v[124:127], v[200:203], v[132:135], v[124:127]
	v_mfma_f32_16x16x32_bf16 v[84:87], v[200:203], v[136:139], v[84:87]
	v_mfma_f32_16x16x32_bf16 v[92:95], v[200:203], v[140:143], v[92:95]
	ds_read_b128 v[200:203], v175 offset:12288
	s_waitcnt lgkmcnt(3)
	v_mfma_f32_16x16x32_bf16 v[96:99], v[204:207], v[128:131], v[96:99]
	v_mfma_f32_16x16x32_bf16 v[104:107], v[204:207], v[132:135], v[104:107]
	v_mfma_f32_16x16x32_bf16 v[64:67], v[204:207], v[136:139], v[64:67]
	v_mfma_f32_16x16x32_bf16 v[72:75], v[204:207], v[140:143], v[72:75]
	ds_read_b128 v[204:207], v174 offset:14336
	s_waitcnt lgkmcnt(3)
	v_mfma_f32_16x16x32_bf16 v[100:103], v[242:245], v[128:131], v[100:103]
	v_mfma_f32_16x16x32_bf16 v[108:111], v[242:245], v[132:135], v[108:111]
	v_mfma_f32_16x16x32_bf16 v[68:71], v[242:245], v[136:139], v[68:71]
	v_mfma_f32_16x16x32_bf16 v[76:79], v[242:245], v[140:143], v[76:79]
	ds_read_b128 v[242:245], v175 offset:14336
	s_waitcnt lgkmcnt(3)
	v_mfma_f32_16x16x32_bf16 v[48:51], v[196:199], v[128:131], v[48:51]
	v_mfma_f32_16x16x32_bf16 v[56:59], v[196:199], v[132:135], v[56:59]
	v_mfma_f32_16x16x32_bf16 v[16:19], v[196:199], v[136:139], v[16:19]
	v_mfma_f32_16x16x32_bf16 v[24:27], v[196:199], v[140:143], v[24:27]
	s_waitcnt lgkmcnt(2)
	v_mfma_f32_16x16x32_bf16 v[52:55], v[200:203], v[128:131], v[52:55]
	v_mfma_f32_16x16x32_bf16 v[60:63], v[200:203], v[132:135], v[60:63]
	v_mfma_f32_16x16x32_bf16 v[20:23], v[200:203], v[136:139], v[20:23]
	v_mfma_f32_16x16x32_bf16 v[28:31], v[200:203], v[140:143], v[28:31]
	s_waitcnt lgkmcnt(1)
	v_mfma_f32_16x16x32_bf16 v[32:35], v[204:207], v[128:131], v[32:35]
	v_mfma_f32_16x16x32_bf16 v[40:43], v[204:207], v[132:135], v[40:43]
	v_mfma_f32_16x16x32_bf16 v[0:3], v[204:207], v[136:139], v[0:3]
	v_mfma_f32_16x16x32_bf16 v[8:11], v[204:207], v[140:143], v[8:11]
	s_waitcnt lgkmcnt(0)
	v_mfma_f32_16x16x32_bf16 v[36:39], v[242:245], v[128:131], v[36:39]
	v_mfma_f32_16x16x32_bf16 v[44:47], v[242:245], v[132:135], v[44:47]
	v_mfma_f32_16x16x32_bf16 v[4:7], v[242:245], v[136:139], v[4:7]
	v_mfma_f32_16x16x32_bf16 v[12:15], v[242:245], v[140:143], v[12:15]
	global_load_dwordx4 v[128:131], v[248:249], off
	global_load_dwordx4 v[132:135], v[248:249], off offset:256
	global_load_dwordx4 v[136:139], v[250:251], off
	global_load_dwordx4 v[140:143], v[250:251], off offset:256
	s_waitcnt vmcnt(10)
	s_barrier
	s_add_i32 s8, s1, 7
	s_lshl_b32 s96, s8, 13
	s_add_i32 m0, vcc_lo, 8192
	v_lshl_add_u64 v[160:161], v[172:173], 0, s[96:97]
	global_load_lds_dwordx4 v[160:161], off
	global_load_lds_dwordx4 v[160:161], off offset:1024
	ds_read_b128 v[196:199], v174 offset:16384
	ds_read_b128 v[200:203], v175 offset:16384
	ds_read_b128 v[204:207], v174 offset:18432
	ds_read_b128 v[242:245], v175 offset:18432
	s_add_i32 s8, s1, 7
	s_lshl_b32 s96, s8, 11
	v_lshl_add_u64 v[248:249], v[168:169], 0, s[96:97]
	v_lshl_add_u64 v[250:251], v[170:171], 0, s[96:97]
	s_waitcnt vmcnt(8) lgkmcnt(3)
	v_mfma_f32_16x16x32_bf16 v[112:115], v[196:199], v[144:147], v[112:115]
	v_mfma_f32_16x16x32_bf16 v[120:123], v[196:199], v[148:151], v[120:123]
	v_mfma_f32_16x16x32_bf16 v[80:83], v[196:199], v[152:155], v[80:83]
	v_mfma_f32_16x16x32_bf16 v[88:91], v[196:199], v[156:159], v[88:91]
	ds_read_b128 v[196:199], v174 offset:20480
	s_waitcnt lgkmcnt(3)
	v_mfma_f32_16x16x32_bf16 v[116:119], v[200:203], v[144:147], v[116:119]
	v_mfma_f32_16x16x32_bf16 v[124:127], v[200:203], v[148:151], v[124:127]
	v_mfma_f32_16x16x32_bf16 v[84:87], v[200:203], v[152:155], v[84:87]
	v_mfma_f32_16x16x32_bf16 v[92:95], v[200:203], v[156:159], v[92:95]
	ds_read_b128 v[200:203], v175 offset:20480
	s_waitcnt lgkmcnt(3)
	v_mfma_f32_16x16x32_bf16 v[96:99], v[204:207], v[144:147], v[96:99]
	v_mfma_f32_16x16x32_bf16 v[104:107], v[204:207], v[148:151], v[104:107]
	v_mfma_f32_16x16x32_bf16 v[64:67], v[204:207], v[152:155], v[64:67]
	v_mfma_f32_16x16x32_bf16 v[72:75], v[204:207], v[156:159], v[72:75]
	ds_read_b128 v[204:207], v174 offset:22528
	s_waitcnt lgkmcnt(3)
	v_mfma_f32_16x16x32_bf16 v[100:103], v[242:245], v[144:147], v[100:103]
	v_mfma_f32_16x16x32_bf16 v[108:111], v[242:245], v[148:151], v[108:111]
	v_mfma_f32_16x16x32_bf16 v[68:71], v[242:245], v[152:155], v[68:71]
	v_mfma_f32_16x16x32_bf16 v[76:79], v[242:245], v[156:159], v[76:79]
	ds_read_b128 v[242:245], v175 offset:22528
	s_waitcnt lgkmcnt(3)
	v_mfma_f32_16x16x32_bf16 v[48:51], v[196:199], v[144:147], v[48:51]
	v_mfma_f32_16x16x32_bf16 v[56:59], v[196:199], v[148:151], v[56:59]
	v_mfma_f32_16x16x32_bf16 v[16:19], v[196:199], v[152:155], v[16:19]
	v_mfma_f32_16x16x32_bf16 v[24:27], v[196:199], v[156:159], v[24:27]
	s_waitcnt lgkmcnt(2)
	v_mfma_f32_16x16x32_bf16 v[52:55], v[200:203], v[144:147], v[52:55]
	v_mfma_f32_16x16x32_bf16 v[60:63], v[200:203], v[148:151], v[60:63]
	v_mfma_f32_16x16x32_bf16 v[20:23], v[200:203], v[152:155], v[20:23]
	v_mfma_f32_16x16x32_bf16 v[28:31], v[200:203], v[156:159], v[28:31]
	s_waitcnt lgkmcnt(1)
	v_mfma_f32_16x16x32_bf16 v[32:35], v[204:207], v[144:147], v[32:35]
	v_mfma_f32_16x16x32_bf16 v[40:43], v[204:207], v[148:151], v[40:43]
	v_mfma_f32_16x16x32_bf16 v[0:3], v[204:207], v[152:155], v[0:3]
	v_mfma_f32_16x16x32_bf16 v[8:11], v[204:207], v[156:159], v[8:11]
	s_waitcnt lgkmcnt(0)
	v_mfma_f32_16x16x32_bf16 v[36:39], v[242:245], v[144:147], v[36:39]
	v_mfma_f32_16x16x32_bf16 v[44:47], v[242:245], v[148:151], v[44:47]
	v_mfma_f32_16x16x32_bf16 v[4:7], v[242:245], v[152:155], v[4:7]
	v_mfma_f32_16x16x32_bf16 v[12:15], v[242:245], v[156:159], v[12:15]
	global_load_dwordx4 v[144:147], v[248:249], off
	global_load_dwordx4 v[148:151], v[248:249], off offset:256
	global_load_dwordx4 v[152:155], v[250:251], off
	global_load_dwordx4 v[156:159], v[250:251], off offset:256
	s_waitcnt vmcnt(10)
	s_barrier
	s_add_i32 s1, s1, 6
	s_cmp_lt_u32 s1, 30
	s_cbranch_scc1 .Lg16_gu_k
	ds_read_b128 v[196:199], v174 offset:0
	ds_read_b128 v[200:203], v175 offset:0
	ds_read_b128 v[204:207], v174 offset:2048
	ds_read_b128 v[242:245], v175 offset:2048
	s_waitcnt vmcnt(6) lgkmcnt(3)
	v_mfma_f32_16x16x32_bf16 v[112:115], v[196:199], v[128:131], v[112:115]
	v_mfma_f32_16x16x32_bf16 v[120:123], v[196:199], v[132:135], v[120:123]
	v_mfma_f32_16x16x32_bf16 v[80:83], v[196:199], v[136:139], v[80:83]
	v_mfma_f32_16x16x32_bf16 v[88:91], v[196:199], v[140:143], v[88:91]
	ds_read_b128 v[196:199], v174 offset:4096
	s_waitcnt lgkmcnt(3)
	v_mfma_f32_16x16x32_bf16 v[116:119], v[200:203], v[128:131], v[116:119]
	v_mfma_f32_16x16x32_bf16 v[124:127], v[200:203], v[132:135], v[124:127]
	v_mfma_f32_16x16x32_bf16 v[84:87], v[200:203], v[136:139], v[84:87]
	v_mfma_f32_16x16x32_bf16 v[92:95], v[200:203], v[140:143], v[92:95]
	ds_read_b128 v[200:203], v175 offset:4096
	s_waitcnt lgkmcnt(3)
	v_mfma_f32_16x16x32_bf16 v[96:99], v[204:207], v[128:131], v[96:99]
	v_mfma_f32_16x16x32_bf16 v[104:107], v[204:207], v[132:135], v[104:107]
	v_mfma_f32_16x16x32_bf16 v[64:67], v[204:207], v[136:139], v[64:67]
	v_mfma_f32_16x16x32_bf16 v[72:75], v[204:207], v[140:143], v[72:75]
	ds_read_b128 v[204:207], v174 offset:6144
	s_waitcnt lgkmcnt(3)
	v_mfma_f32_16x16x32_bf16 v[100:103], v[242:245], v[128:131], v[100:103]
	v_mfma_f32_16x16x32_bf16 v[108:111], v[242:245], v[132:135], v[108:111]
	v_mfma_f32_16x16x32_bf16 v[68:71], v[242:245], v[136:139], v[68:71]
	v_mfma_f32_16x16x32_bf16 v[76:79], v[242:245], v[140:143], v[76:79]
	ds_read_b128 v[242:245], v175 offset:6144
	s_waitcnt lgkmcnt(3)
	v_mfma_f32_16x16x32_bf16 v[48:51], v[196:199], v[128:131], v[48:51]
	v_mfma_f32_16x16x32_bf16 v[56:59], v[196:199], v[132:135], v[56:59]
	v_mfma_f32_16x16x32_bf16 v[16:19], v[196:199], v[136:139], v[16:19]
	v_mfma_f32_16x16x32_bf16 v[24:27], v[196:199], v[140:143], v[24:27]
	s_waitcnt lgkmcnt(2)
	v_mfma_f32_16x16x32_bf16 v[52:55], v[200:203], v[128:131], v[52:55]
	v_mfma_f32_16x16x32_bf16 v[60:63], v[200:203], v[132:135], v[60:63]
	v_mfma_f32_16x16x32_bf16 v[20:23], v[200:203], v[136:139], v[20:23]
	v_mfma_f32_16x16x32_bf16 v[28:31], v[200:203], v[140:143], v[28:31]
	s_waitcnt lgkmcnt(1)
	v_mfma_f32_16x16x32_bf16 v[32:35], v[204:207], v[128:131], v[32:35]
	v_mfma_f32_16x16x32_bf16 v[40:43], v[204:207], v[132:135], v[40:43]
	v_mfma_f32_16x16x32_bf16 v[0:3], v[204:207], v[136:139], v[0:3]
	v_mfma_f32_16x16x32_bf16 v[8:11], v[204:207], v[140:143], v[8:11]
	s_waitcnt lgkmcnt(0)
	v_mfma_f32_16x16x32_bf16 v[36:39], v[242:245], v[128:131], v[36:39]
	v_mfma_f32_16x16x32_bf16 v[44:47], v[242:245], v[132:135], v[44:47]
	v_mfma_f32_16x16x32_bf16 v[4:7], v[242:245], v[136:139], v[4:7]
	v_mfma_f32_16x16x32_bf16 v[12:15], v[242:245], v[140:143], v[12:15]
	s_waitcnt vmcnt(4)
	s_barrier
	ds_read_b128 v[196:199], v174 offset:8192
	ds_read_b128 v[200:203], v175 offset:8192
	ds_read_b128 v[204:207], v174 offset:10240
	ds_read_b128 v[242:245], v175 offset:10240
	s_waitcnt vmcnt(0) lgkmcnt(3)
	v_mfma_f32_16x16x32_bf16 v[112:115], v[196:199], v[144:147], v[112:115]
	v_mfma_f32_16x16x32_bf16 v[120:123], v[196:199], v[148:151], v[120:123]
	v_mfma_f32_16x16x32_bf16 v[80:83], v[196:199], v[152:155], v[80:83]
	v_mfma_f32_16x16x32_bf16 v[88:91], v[196:199], v[156:159], v[88:91]
	ds_read_b128 v[196:199], v174 offset:12288
	s_waitcnt lgkmcnt(3)
	v_mfma_f32_16x16x32_bf16 v[116:119], v[200:203], v[144:147], v[116:119]
	v_mfma_f32_16x16x32_bf16 v[124:127], v[200:203], v[148:151], v[124:127]
	v_mfma_f32_16x16x32_bf16 v[84:87], v[200:203], v[152:155], v[84:87]
	v_mfma_f32_16x16x32_bf16 v[92:95], v[200:203], v[156:159], v[92:95]
	ds_read_b128 v[200:203], v175 offset:12288
	s_waitcnt lgkmcnt(3)
	v_mfma_f32_16x16x32_bf16 v[96:99], v[204:207], v[144:147], v[96:99]
	v_mfma_f32_16x16x32_bf16 v[104:107], v[204:207], v[148:151], v[104:107]
	v_mfma_f32_16x16x32_bf16 v[64:67], v[204:207], v[152:155], v[64:67]
	v_mfma_f32_16x16x32_bf16 v[72:75], v[204:207], v[156:159], v[72:75]
	ds_read_b128 v[204:207], v174 offset:14336
	s_waitcnt lgkmcnt(3)
	v_mfma_f32_16x16x32_bf16 v[100:103], v[242:245], v[144:147], v[100:103]
	v_mfma_f32_16x16x32_bf16 v[108:111], v[242:245], v[148:151], v[108:111]
	v_mfma_f32_16x16x32_bf16 v[68:71], v[242:245], v[152:155], v[68:71]
	v_mfma_f32_16x16x32_bf16 v[76:79], v[242:245], v[156:159], v[76:79]
	ds_read_b128 v[242:245], v175 offset:14336
	s_waitcnt lgkmcnt(3)
	v_mfma_f32_16x16x32_bf16 v[48:51], v[196:199], v[144:147], v[48:51]
	v_mfma_f32_16x16x32_bf16 v[56:59], v[196:199], v[148:151], v[56:59]
	v_mfma_f32_16x16x32_bf16 v[16:19], v[196:199], v[152:155], v[16:19]
	v_mfma_f32_16x16x32_bf16 v[24:27], v[196:199], v[156:159], v[24:27]
	s_waitcnt lgkmcnt(2)
	v_mfma_f32_16x16x32_bf16 v[52:55], v[200:203], v[144:147], v[52:55]
	v_mfma_f32_16x16x32_bf16 v[60:63], v[200:203], v[148:151], v[60:63]
	v_mfma_f32_16x16x32_bf16 v[20:23], v[200:203], v[152:155], v[20:23]
	v_mfma_f32_16x16x32_bf16 v[28:31], v[200:203], v[156:159], v[28:31]
	s_waitcnt lgkmcnt(1)
	v_mfma_f32_16x16x32_bf16 v[32:35], v[204:207], v[144:147], v[32:35]
	v_mfma_f32_16x16x32_bf16 v[40:43], v[204:207], v[148:151], v[40:43]
	v_mfma_f32_16x16x32_bf16 v[0:3], v[204:207], v[152:155], v[0:3]
	v_mfma_f32_16x16x32_bf16 v[8:11], v[204:207], v[156:159], v[8:11]
	s_waitcnt lgkmcnt(0)
	v_mfma_f32_16x16x32_bf16 v[36:39], v[242:245], v[144:147], v[36:39]
	v_mfma_f32_16x16x32_bf16 v[44:47], v[242:245], v[148:151], v[44:47]
	v_mfma_f32_16x16x32_bf16 v[4:7], v[242:245], v[152:155], v[4:7]
	v_mfma_f32_16x16x32_bf16 v[12:15], v[242:245], v[156:159], v[12:15]
	s_barrier
	v_readlane_b32 s8, v254, 11
	s_mov_b32 s99, 0
	s_add_i32 s8, s2, s8
	s_cmp_ge_i32 s8, s3
	s_cbranch_scc1 .Lg16_gu_np
	s_mul_hi_i32 s9, s8, 0x2e8ba2e9
	s_ashr_i32 s9, s9, 6
	s_lshl_b32 s1, s9, 3
	s_sub_i32 s96, s25, s1
	s_mulk_i32 s9, 0x160
	s_sub_i32 s8, s8, s9
	s_cmp_ge_i32 s96, 8
	s_cbranch_scc1 .Lg16_gu_gs8
	s_cmp_eq_u32 s96, 1
	s_cbranch_scc0 .Lg16_gu_np
	s_mov_b32 s9, 0
	s_branch .Lg16_gu_have

.Lg16_gu_have:
	s_add_i32 s9, s9, s1
	s_add_i32 s9, s9, s6
	s_sub_i32 s9, s9, s7
	s_lshl_b32 s9, s9, 19
	s_sub_i32 s8, s8, s0
	s_lshl_b32 s1, s8, 18
	s_mov_b32 s8, s9
	s_ashr_i32 s9, s9, 31
	v_lshl_add_u64 v[168:169], v[168:169], 0, s[8:9]
	v_lshl_add_u64 v[170:171], v[170:171], 0, s[8:9]
	s_mov_b32 s8, s1
	s_ashr_i32 s9, s1, 31
	v_lshl_add_u64 v[172:173], v[172:173], 0, s[8:9]
	s_mov_b32 s96, 0
	s_mov_b32 m0, vcc_lo
	v_lshl_add_u64 v[160:161], v[172:173], 0, s[96:97]
	global_load_lds_dwordx4 v[160:161], off
	global_load_lds_dwordx4 v[160:161], off offset:1024
	s_mov_b32 s96, 0
	v_lshl_add_u64 v[248:249], v[168:169], 0, s[96:97]
	v_lshl_add_u64 v[250:251], v[170:171], 0, s[96:97]
	global_load_dwordx4 v[128:131], v[248:249], off
	global_load_dwordx4 v[132:135], v[248:249], off offset:256
	global_load_dwordx4 v[136:139], v[250:251], off
	global_load_dwordx4 v[140:143], v[250:251], off offset:256
	s_movk_i32 s96, 0x2000
	s_add_i32 m0, vcc_lo, 8192
	v_lshl_add_u64 v[160:161], v[172:173], 0, s[96:97]
	global_load_lds_dwordx4 v[160:161], off
	global_load_lds_dwordx4 v[160:161], off offset:1024
	s_movk_i32 s96, 0x800
	v_lshl_add_u64 v[248:249], v[168:169], 0, s[96:97]
	v_lshl_add_u64 v[250:251], v[170:171], 0, s[96:97]
	global_load_dwordx4 v[144:147], v[248:249], off
	global_load_dwordx4 v[148:151], v[248:249], off offset:256
	global_load_dwordx4 v[152:155], v[250:251], off
	global_load_dwordx4 v[156:159], v[250:251], off offset:256
	s_mov_b32 s99, 1
.Lg16_gu_np:
	s_nop 7
	s_nop 1
	v_and_b32_e32 v163, 63, v179
	v_lshrrev_b32_e32 v164, 6, v179
	s_lshl_b32 s14, s7, 3
	s_mul_hi_u32 s15, s14, 0x2c000
	s_mul_i32 s14, s14, 0x2c000
	s_lshl_b32 s16, s0, 12
	s_add_u32 s12, s66, s14
	s_addc_u32 s13, s67, s15
	s_add_u32 s12, s12, s16
	s_addc_u32 s13, s13, 0
	v_and_b32_e32 v165, 15, v163
	v_lshlrev_b32_e32 v166, 4, v165
	v_lshrrev_b32_e32 v165, 4, v163
	v_lshl_add_u32 v166, v165, 9, v166
	v_mul_u32_u24_e32 v165, 0x58000, v164
	v_add_u32_e32 v166, v166, v165
	v_add_u32_e32 v167, 0x2c000, v166
	v_mul_f32_e32 v196, 0xbfb8aa3b, v112
	v_mul_f32_e32 v197, 0xbfb8aa3b, v113
	v_mul_f32_e32 v198, 0xbfb8aa3b, v114
	v_mul_f32_e32 v199, 0xbfb8aa3b, v115
	v_mul_f32_e32 v200, 0xbfb8aa3b, v116
	v_mul_f32_e32 v201, 0xbfb8aa3b, v117
	v_mul_f32_e32 v202, 0xbfb8aa3b, v118
	v_mul_f32_e32 v203, 0xbfb8aa3b, v119
	v_exp_f32_e32 v196, v196
	v_exp_f32_e32 v197, v197
	v_exp_f32_e32 v198, v198
	v_exp_f32_e32 v199, v199
	v_exp_f32_e32 v200, v200
	v_exp_f32_e32 v201, v201
	v_exp_f32_e32 v202, v202
	v_exp_f32_e32 v203, v203
	v_add_f32_e32 v196, 1.0, v196
	v_add_f32_e32 v197, 1.0, v197
	v_add_f32_e32 v198, 1.0, v198
	v_add_f32_e32 v199, 1.0, v199
	v_add_f32_e32 v200, 1.0, v200
	v_add_f32_e32 v201, 1.0, v201
	v_add_f32_e32 v202, 1.0, v202
	v_add_f32_e32 v203, 1.0, v203
	v_rcp_f32_e32 v196, v196
	v_rcp_f32_e32 v197, v197
	v_rcp_f32_e32 v198, v198
	v_rcp_f32_e32 v199, v199
	v_rcp_f32_e32 v200, v200
	v_rcp_f32_e32 v201, v201
	v_rcp_f32_e32 v202, v202
	v_rcp_f32_e32 v203, v203
	v_mul_f32_e32 v196, v112, v196
	v_mul_f32_e32 v197, v113, v197
	v_mul_f32_e32 v198, v114, v198
	v_mul_f32_e32 v199, v115, v199
	v_mul_f32_e32 v200, v116, v200
	v_mul_f32_e32 v201, v117, v201
	v_mul_f32_e32 v202, v118, v202
	v_mul_f32_e32 v203, v119, v203
	v_mul_f32_e32 v196, v96, v196
	v_mul_f32_e32 v197, v97, v197
	v_mul_f32_e32 v198, v98, v198
	v_mul_f32_e32 v199, v99, v199
	v_mul_f32_e32 v200, v100, v200
	v_mul_f32_e32 v201, v101, v201
	v_mul_f32_e32 v202, v102, v202
	v_mul_f32_e32 v203, v103, v203
	v_cvt_pk_bf16_f32 v204, v196, v197
	v_cvt_pk_bf16_f32 v205, v198, v199
	v_cvt_pk_bf16_f32 v206, v200, v201
	v_cvt_pk_bf16_f32 v207, v202, v203
	global_store_dwordx4 v166, v[204:207], s[12:13]
	v_mul_f32_e32 v196, 0xbfb8aa3b, v120
	v_mul_f32_e32 v197, 0xbfb8aa3b, v121
	v_mul_f32_e32 v198, 0xbfb8aa3b, v122
	v_mul_f32_e32 v199, 0xbfb8aa3b, v123
	v_mul_f32_e32 v200, 0xbfb8aa3b, v124
	v_mul_f32_e32 v201, 0xbfb8aa3b, v125
	v_mul_f32_e32 v202, 0xbfb8aa3b, v126
	v_mul_f32_e32 v203, 0xbfb8aa3b, v127
	v_exp_f32_e32 v196, v196
	v_exp_f32_e32 v197, v197
	v_exp_f32_e32 v198, v198
	v_exp_f32_e32 v199, v199
	v_exp_f32_e32 v200, v200
	v_exp_f32_e32 v201, v201
	v_exp_f32_e32 v202, v202
	v_exp_f32_e32 v203, v203
	v_add_f32_e32 v196, 1.0, v196
	v_add_f32_e32 v197, 1.0, v197
	v_add_f32_e32 v198, 1.0, v198
	v_add_f32_e32 v199, 1.0, v199
	v_add_f32_e32 v200, 1.0, v200
	v_add_f32_e32 v201, 1.0, v201
	v_add_f32_e32 v202, 1.0, v202
	v_add_f32_e32 v203, 1.0, v203
	v_rcp_f32_e32 v196, v196
	v_rcp_f32_e32 v197, v197
	v_rcp_f32_e32 v198, v198
	v_rcp_f32_e32 v199, v199
	v_rcp_f32_e32 v200, v200
	v_rcp_f32_e32 v201, v201
	v_rcp_f32_e32 v202, v202
	v_rcp_f32_e32 v203, v203
	v_mul_f32_e32 v196, v120, v196
	v_mul_f32_e32 v197, v121, v197
	v_mul_f32_e32 v198, v122, v198
	v_mul_f32_e32 v199, v123, v199
	v_mul_f32_e32 v200, v124, v200
	v_mul_f32_e32 v201, v125, v201
	v_mul_f32_e32 v202, v126, v202
	v_mul_f32_e32 v203, v127, v203
	v_mul_f32_e32 v196, v104, v196
	v_mul_f32_e32 v197, v105, v197
	v_mul_f32_e32 v198, v106, v198
	v_mul_f32_e32 v199, v107, v199
	v_mul_f32_e32 v200, v108, v200
	v_mul_f32_e32 v201, v109, v201
	v_mul_f32_e32 v202, v110, v202
	v_mul_f32_e32 v203, v111, v203
	v_cvt_pk_bf16_f32 v242, v196, v197
	v_cvt_pk_bf16_f32 v243, v198, v199
	v_cvt_pk_bf16_f32 v244, v200, v201
	v_cvt_pk_bf16_f32 v245, v202, v203
	global_store_dwordx4 v166, v[242:245], s[12:13] offset:256
	v_mul_f32_e32 v196, 0xbfb8aa3b, v80
	v_mul_f32_e32 v197, 0xbfb8aa3b, v81
	v_mul_f32_e32 v198, 0xbfb8aa3b, v82
	v_mul_f32_e32 v199, 0xbfb8aa3b, v83
	v_mul_f32_e32 v200, 0xbfb8aa3b, v84
	v_mul_f32_e32 v201, 0xbfb8aa3b, v85
	v_mul_f32_e32 v202, 0xbfb8aa3b, v86
	v_mul_f32_e32 v203, 0xbfb8aa3b, v87
	v_exp_f32_e32 v196, v196
	v_exp_f32_e32 v197, v197
	v_exp_f32_e32 v198, v198
	v_exp_f32_e32 v199, v199
	v_exp_f32_e32 v200, v200
	v_exp_f32_e32 v201, v201
	v_exp_f32_e32 v202, v202
	v_exp_f32_e32 v203, v203
	v_add_f32_e32 v196, 1.0, v196
	v_add_f32_e32 v197, 1.0, v197
	v_add_f32_e32 v198, 1.0, v198
	v_add_f32_e32 v199, 1.0, v199
	v_add_f32_e32 v200, 1.0, v200
	v_add_f32_e32 v201, 1.0, v201
	v_add_f32_e32 v202, 1.0, v202
	v_add_f32_e32 v203, 1.0, v203
	v_rcp_f32_e32 v196, v196
	v_rcp_f32_e32 v197, v197
	v_rcp_f32_e32 v198, v198
	v_rcp_f32_e32 v199, v199
	v_rcp_f32_e32 v200, v200
	v_rcp_f32_e32 v201, v201
	v_rcp_f32_e32 v202, v202
	v_rcp_f32_e32 v203, v203
	v_mul_f32_e32 v196, v80, v196
	v_mul_f32_e32 v197, v81, v197
	v_mul_f32_e32 v198, v82, v198
	v_mul_f32_e32 v199, v83, v199
	v_mul_f32_e32 v200, v84, v200
	v_mul_f32_e32 v201, v85, v201
	v_mul_f32_e32 v202, v86, v202
	v_mul_f32_e32 v203, v87, v203
	v_mul_f32_e32 v196, v64, v196
	v_mul_f32_e32 v197, v65, v197
	v_mul_f32_e32 v198, v66, v198
	v_mul_f32_e32 v199, v67, v199
	v_mul_f32_e32 v200, v68, v200
	v_mul_f32_e32 v201, v69, v201
	v_mul_f32_e32 v202, v70, v202
	v_mul_f32_e32 v203, v71, v203
	v_cvt_pk_bf16_f32 v204, v196, v197
	v_cvt_pk_bf16_f32 v205, v198, v199
	v_cvt_pk_bf16_f32 v206, v200, v201
	v_cvt_pk_bf16_f32 v207, v202, v203
	global_store_dwordx4 v167, v[204:207], s[12:13]
	v_mul_f32_e32 v196, 0xbfb8aa3b, v88
	v_mul_f32_e32 v197, 0xbfb8aa3b, v89
	v_mul_f32_e32 v198, 0xbfb8aa3b, v90
	v_mul_f32_e32 v199, 0xbfb8aa3b, v91
	v_mul_f32_e32 v200, 0xbfb8aa3b, v92
	v_mul_f32_e32 v201, 0xbfb8aa3b, v93
	v_mul_f32_e32 v202, 0xbfb8aa3b, v94
	v_mul_f32_e32 v203, 0xbfb8aa3b, v95
	v_exp_f32_e32 v196, v196
	v_exp_f32_e32 v197, v197
	v_exp_f32_e32 v198, v198
	v_exp_f32_e32 v199, v199
	v_exp_f32_e32 v200, v200
	v_exp_f32_e32 v201, v201
	v_exp_f32_e32 v202, v202
	v_exp_f32_e32 v203, v203
	v_add_f32_e32 v196, 1.0, v196
	v_add_f32_e32 v197, 1.0, v197
	v_add_f32_e32 v198, 1.0, v198
	v_add_f32_e32 v199, 1.0, v199
	v_add_f32_e32 v200, 1.0, v200
	v_add_f32_e32 v201, 1.0, v201
	v_add_f32_e32 v202, 1.0, v202
	v_add_f32_e32 v203, 1.0, v203
	v_rcp_f32_e32 v196, v196
	v_rcp_f32_e32 v197, v197
	v_rcp_f32_e32 v198, v198
	v_rcp_f32_e32 v199, v199
	v_rcp_f32_e32 v200, v200
	v_rcp_f32_e32 v201, v201
	v_rcp_f32_e32 v202, v202
	v_rcp_f32_e32 v203, v203
	v_mul_f32_e32 v196, v88, v196
	v_mul_f32_e32 v197, v89, v197
	v_mul_f32_e32 v198, v90, v198
	v_mul_f32_e32 v199, v91, v199
	v_mul_f32_e32 v200, v92, v200
	v_mul_f32_e32 v201, v93, v201
	v_mul_f32_e32 v202, v94, v202
	v_mul_f32_e32 v203, v95, v203
	v_mul_f32_e32 v196, v72, v196
	v_mul_f32_e32 v197, v73, v197
	v_mul_f32_e32 v198, v74, v198
	v_mul_f32_e32 v199, v75, v199
	v_mul_f32_e32 v200, v76, v200
	v_mul_f32_e32 v201, v77, v201
	v_mul_f32_e32 v202, v78, v202
	v_mul_f32_e32 v203, v79, v203
	v_cvt_pk_bf16_f32 v242, v196, v197
	v_cvt_pk_bf16_f32 v243, v198, v199
	v_cvt_pk_bf16_f32 v244, v200, v201
	v_cvt_pk_bf16_f32 v245, v202, v203
	global_store_dwordx4 v167, v[242:245], s[12:13] offset:256
	v_mul_f32_e32 v196, 0xbfb8aa3b, v48
	v_mul_f32_e32 v197, 0xbfb8aa3b, v49
	v_mul_f32_e32 v198, 0xbfb8aa3b, v50
	v_mul_f32_e32 v199, 0xbfb8aa3b, v51
	v_mul_f32_e32 v200, 0xbfb8aa3b, v52
	v_mul_f32_e32 v201, 0xbfb8aa3b, v53
	v_mul_f32_e32 v202, 0xbfb8aa3b, v54
	v_mul_f32_e32 v203, 0xbfb8aa3b, v55
	v_exp_f32_e32 v196, v196
	v_exp_f32_e32 v197, v197
	v_exp_f32_e32 v198, v198
	v_exp_f32_e32 v199, v199
	v_exp_f32_e32 v200, v200
	v_exp_f32_e32 v201, v201
	v_exp_f32_e32 v202, v202
	v_exp_f32_e32 v203, v203
	v_add_f32_e32 v196, 1.0, v196
	v_add_f32_e32 v197, 1.0, v197
	v_add_f32_e32 v198, 1.0, v198
	v_add_f32_e32 v199, 1.0, v199
	v_add_f32_e32 v200, 1.0, v200
	v_add_f32_e32 v201, 1.0, v201
	v_add_f32_e32 v202, 1.0, v202
	v_add_f32_e32 v203, 1.0, v203
	v_rcp_f32_e32 v196, v196
	v_rcp_f32_e32 v197, v197
	v_rcp_f32_e32 v198, v198
	v_rcp_f32_e32 v199, v199
	v_rcp_f32_e32 v200, v200
	v_rcp_f32_e32 v201, v201
	v_rcp_f32_e32 v202, v202
	v_rcp_f32_e32 v203, v203
	v_mul_f32_e32 v196, v48, v196
	v_mul_f32_e32 v197, v49, v197
	v_mul_f32_e32 v198, v50, v198
	v_mul_f32_e32 v199, v51, v199
	v_mul_f32_e32 v200, v52, v200
	v_mul_f32_e32 v201, v53, v201
	v_mul_f32_e32 v202, v54, v202
	v_mul_f32_e32 v203, v55, v203
	v_mul_f32_e32 v196, v32, v196
	v_mul_f32_e32 v197, v33, v197
	v_mul_f32_e32 v198, v34, v198
	v_mul_f32_e32 v199, v35, v199
	v_mul_f32_e32 v200, v36, v200
	v_mul_f32_e32 v201, v37, v201
	v_mul_f32_e32 v202, v38, v202
	v_mul_f32_e32 v203, v39, v203
	v_cvt_pk_bf16_f32 v204, v196, v197
	v_cvt_pk_bf16_f32 v205, v198, v199
	v_cvt_pk_bf16_f32 v206, v200, v201
	v_cvt_pk_bf16_f32 v207, v202, v203
	global_store_dwordx4 v166, v[204:207], s[12:13] offset:2048
	v_mul_f32_e32 v196, 0xbfb8aa3b, v56
	v_mul_f32_e32 v197, 0xbfb8aa3b, v57
	v_mul_f32_e32 v198, 0xbfb8aa3b, v58
	v_mul_f32_e32 v199, 0xbfb8aa3b, v59
	v_mul_f32_e32 v200, 0xbfb8aa3b, v60
	v_mul_f32_e32 v201, 0xbfb8aa3b, v61
	v_mul_f32_e32 v202, 0xbfb8aa3b, v62
	v_mul_f32_e32 v203, 0xbfb8aa3b, v63
	v_exp_f32_e32 v196, v196
	v_exp_f32_e32 v197, v197
	v_exp_f32_e32 v198, v198
	v_exp_f32_e32 v199, v199
	v_exp_f32_e32 v200, v200
	v_exp_f32_e32 v201, v201
	v_exp_f32_e32 v202, v202
	v_exp_f32_e32 v203, v203
	v_add_f32_e32 v196, 1.0, v196
	v_add_f32_e32 v197, 1.0, v197
	v_add_f32_e32 v198, 1.0, v198
	v_add_f32_e32 v199, 1.0, v199
	v_add_f32_e32 v200, 1.0, v200
	v_add_f32_e32 v201, 1.0, v201
	v_add_f32_e32 v202, 1.0, v202
	v_add_f32_e32 v203, 1.0, v203
	v_rcp_f32_e32 v196, v196
	v_rcp_f32_e32 v197, v197
	v_rcp_f32_e32 v198, v198
	v_rcp_f32_e32 v199, v199
	v_rcp_f32_e32 v200, v200
	v_rcp_f32_e32 v201, v201
	v_rcp_f32_e32 v202, v202
	v_rcp_f32_e32 v203, v203
	v_mul_f32_e32 v196, v56, v196
	v_mul_f32_e32 v197, v57, v197
	v_mul_f32_e32 v198, v58, v198
	v_mul_f32_e32 v199, v59, v199
	v_mul_f32_e32 v200, v60, v200
	v_mul_f32_e32 v201, v61, v201
	v_mul_f32_e32 v202, v62, v202
	v_mul_f32_e32 v203, v63, v203
	v_mul_f32_e32 v196, v40, v196
	v_mul_f32_e32 v197, v41, v197
	v_mul_f32_e32 v198, v42, v198
	v_mul_f32_e32 v199, v43, v199
	v_mul_f32_e32 v200, v44, v200
	v_mul_f32_e32 v201, v45, v201
	v_mul_f32_e32 v202, v46, v202
	v_mul_f32_e32 v203, v47, v203
	v_cvt_pk_bf16_f32 v242, v196, v197
	v_cvt_pk_bf16_f32 v243, v198, v199
	v_cvt_pk_bf16_f32 v244, v200, v201
	v_cvt_pk_bf16_f32 v245, v202, v203
	global_store_dwordx4 v166, v[242:245], s[12:13] offset:2304
	v_mul_f32_e32 v196, 0xbfb8aa3b, v16
	v_mul_f32_e32 v197, 0xbfb8aa3b, v17
	v_mul_f32_e32 v198, 0xbfb8aa3b, v18
	v_mul_f32_e32 v199, 0xbfb8aa3b, v19
	v_mul_f32_e32 v200, 0xbfb8aa3b, v20
	v_mul_f32_e32 v201, 0xbfb8aa3b, v21
	v_mul_f32_e32 v202, 0xbfb8aa3b, v22
	v_mul_f32_e32 v203, 0xbfb8aa3b, v23
	v_exp_f32_e32 v196, v196
	v_exp_f32_e32 v197, v197
	v_exp_f32_e32 v198, v198
	v_exp_f32_e32 v199, v199
	v_exp_f32_e32 v200, v200
	v_exp_f32_e32 v201, v201
	v_exp_f32_e32 v202, v202
	v_exp_f32_e32 v203, v203
	v_add_f32_e32 v196, 1.0, v196
	v_add_f32_e32 v197, 1.0, v197
	v_add_f32_e32 v198, 1.0, v198
	v_add_f32_e32 v199, 1.0, v199
	v_add_f32_e32 v200, 1.0, v200
	v_add_f32_e32 v201, 1.0, v201
	v_add_f32_e32 v202, 1.0, v202
	v_add_f32_e32 v203, 1.0, v203
	v_rcp_f32_e32 v196, v196
	v_rcp_f32_e32 v197, v197
	v_rcp_f32_e32 v198, v198
	v_rcp_f32_e32 v199, v199
	v_rcp_f32_e32 v200, v200
	v_rcp_f32_e32 v201, v201
	v_rcp_f32_e32 v202, v202
	v_rcp_f32_e32 v203, v203
	v_mul_f32_e32 v196, v16, v196
	v_mul_f32_e32 v197, v17, v197
	v_mul_f32_e32 v198, v18, v198
	v_mul_f32_e32 v199, v19, v199
	v_mul_f32_e32 v200, v20, v200
	v_mul_f32_e32 v201, v21, v201
	v_mul_f32_e32 v202, v22, v202
	v_mul_f32_e32 v203, v23, v203
	v_mul_f32_e32 v196, v0, v196
	v_mul_f32_e32 v197, v1, v197
	v_mul_f32_e32 v198, v2, v198
	v_mul_f32_e32 v199, v3, v199
	v_mul_f32_e32 v200, v4, v200
	v_mul_f32_e32 v201, v5, v201
	v_mul_f32_e32 v202, v6, v202
	v_mul_f32_e32 v203, v7, v203
	v_cvt_pk_bf16_f32 v204, v196, v197
	v_cvt_pk_bf16_f32 v205, v198, v199
	v_cvt_pk_bf16_f32 v206, v200, v201
	v_cvt_pk_bf16_f32 v207, v202, v203
	global_store_dwordx4 v167, v[204:207], s[12:13] offset:2048
	v_mul_f32_e32 v196, 0xbfb8aa3b, v24
	v_mul_f32_e32 v197, 0xbfb8aa3b, v25
	v_mul_f32_e32 v198, 0xbfb8aa3b, v26
	v_mul_f32_e32 v199, 0xbfb8aa3b, v27
	v_mul_f32_e32 v200, 0xbfb8aa3b, v28
	v_mul_f32_e32 v201, 0xbfb8aa3b, v29
	v_mul_f32_e32 v202, 0xbfb8aa3b, v30
	v_mul_f32_e32 v203, 0xbfb8aa3b, v31
	v_exp_f32_e32 v196, v196
	v_exp_f32_e32 v197, v197
	v_exp_f32_e32 v198, v198
	v_exp_f32_e32 v199, v199
	v_exp_f32_e32 v200, v200
	v_exp_f32_e32 v201, v201
	v_exp_f32_e32 v202, v202
	v_exp_f32_e32 v203, v203
	v_add_f32_e32 v196, 1.0, v196
	v_add_f32_e32 v197, 1.0, v197
	v_add_f32_e32 v198, 1.0, v198
	v_add_f32_e32 v199, 1.0, v199
	v_add_f32_e32 v200, 1.0, v200
	v_add_f32_e32 v201, 1.0, v201
	v_add_f32_e32 v202, 1.0, v202
	v_add_f32_e32 v203, 1.0, v203
	v_rcp_f32_e32 v196, v196
	v_rcp_f32_e32 v197, v197
	v_rcp_f32_e32 v198, v198
	v_rcp_f32_e32 v199, v199
	v_rcp_f32_e32 v200, v200
	v_rcp_f32_e32 v201, v201
	v_rcp_f32_e32 v202, v202
	v_rcp_f32_e32 v203, v203
	v_mul_f32_e32 v196, v24, v196
	v_mul_f32_e32 v197, v25, v197
	v_mul_f32_e32 v198, v26, v198
	v_mul_f32_e32 v199, v27, v199
	v_mul_f32_e32 v200, v28, v200
	v_mul_f32_e32 v201, v29, v201
	v_mul_f32_e32 v202, v30, v202
	v_mul_f32_e32 v203, v31, v203
	v_mul_f32_e32 v196, v8, v196
	v_mul_f32_e32 v197, v9, v197
	v_mul_f32_e32 v198, v10, v198
	v_mul_f32_e32 v199, v11, v199
	v_mul_f32_e32 v200, v12, v200
	v_mul_f32_e32 v201, v13, v201
	v_mul_f32_e32 v202, v14, v202
	v_mul_f32_e32 v203, v15, v203
	v_cvt_pk_bf16_f32 v242, v196, v197
	v_cvt_pk_bf16_f32 v243, v198, v199
	v_cvt_pk_bf16_f32 v244, v200, v201
	v_cvt_pk_bf16_f32 v245, v202, v203
	global_store_dwordx4 v167, v[242:245], s[12:13] offset:2304
	v_readlane_b32 s0, v254, 11
	s_add_i32 s2, s2, s0
	s_cmp_lt_i32 s2, s3
	s_barrier
	s_cbranch_scc1 .LBB0_1031
